# phase-start scalar loads behind one wait; EpiF all-ones scale materialised as constants (no load wait behind the DMA queue)
# baseline (speedup 1.0000x reference)
.LBB0_40:
	s_bitcmp1_b32 s3, 0
	s_cselect_b64 s[16:17], -1, 0
	s_and_b64 vcc, exec, s[16:17]
	s_cbranch_vccnz .LBB0_9
	s_mov_b64 s[26:27], s[0:1]
	v_mov_b32_e32 v208, v228
	s_load_dword s12, s[0:1], 0x78
	s_mov_b32 s28, s70
	s_load_dwordx16 s[52:67], s[26:27], 0x0
	s_load_dwordx2 s[24:25], s[26:27], 0x60
	s_load_dwordx8 s[36:43], s[26:27], 0x40
	s_lshl_b32 s2, s14, 1
	s_add_i32 s6, s13, -4
	s_cmp_lt_u32 s6, 3
	s_cselect_b64 s[16:17], -1, 0
	v_cndmask_b32_e64 v0, 0, 1, s[16:17]
	s_waitcnt lgkmcnt(0)
	v_writelane_b32 v255, s36, 21
	v_readfirstlane_b32 s6, v0
	s_or_b32 s2, s2, s6
	v_writelane_b32 v255, s37, 22
	v_writelane_b32 v255, s38, 23
	s_add_i32 s2, s2, -1
	v_writelane_b32 v255, s39, 24
	s_cmp_lt_u32 s2, 4
	v_writelane_b32 v255, s40, 25
	s_cselect_b64 s[30:31], -1, 0
	v_writelane_b32 v255, s41, 26
	s_and_b64 s[16:17], s[30:31], exec
	v_writelane_b32 v255, s42, 27
	s_cselect_b32 s2, 0x1a0fa400, 0
	v_writelane_b32 v255, s43, 28
	s_add_u32 s36, s24, s2
	s_addc_u32 s37, s25, 0
	s_and_b64 s[16:17], s[30:31], exec
	s_cselect_b32 s2, s71, 0x19680000
	s_add_u32 s86, s24, s2
	s_addc_u32 s87, s25, 0
	s_add_u32 s84, s24, 0x8100000
	s_addc_u32 s85, s25, 0
	s_ashr_i32 s82, s14, 1
	s_cmp_lt_i32 s13, 5
	s_mov_b64 s[26:27], -1
	s_cbranch_scc1 .LBB0_229
	s_cmp_lt_i32 s13, 7
	s_cbranch_scc1 .LBB0_46
	s_cmp_gt_i32 s13, 7
	s_cbranch_scc0 .LBB0_47
	s_cmp_gt_i32 s13, 8
	s_cbranch_scc0 .LBB0_48
	s_cmp_eq_u32 s13, 9
	s_cselect_b64 s[40:41], -1, 0
	s_cbranch_execz .LBB0_49
	s_branch .LBB0_65

.LBB0_191:
	v_mov_b32_e32 v158, v160
	s_mov_b32 s40, s16
	v_mov_b32_e32 v159, v161
	s_mov_b32 s92, s23
	s_lshl_b32 s41, s48, 8
	s_lshl_b32 s48, s99, 8
	s_lshl_b32 s68, s92, 5
	s_add_i32 s68, s68, s48
	v_lshl_add_u32 v156, v159, 3, s68
	v_ashrrev_i32_e32 v157, 31, v156
	v_lshl_add_u64 v[110:111], v[156:157], 2, s[44:45]
	v_mov_b32_e32 v122, 1.0
	v_mov_b32_e32 v123, 1.0
	v_mov_b32_e32 v124, 1.0
	v_mov_b32_e32 v125, 1.0
	v_mov_b32_e32 v126, 1.0
	v_mov_b32_e32 v127, 1.0
	v_mov_b32_e32 v128, 1.0
	v_mov_b32_e32 v129, 1.0
	v_mov_b32_e32 v106, 1.0
	v_mov_b32_e32 v107, 1.0
	v_mov_b32_e32 v108, 1.0
	v_mov_b32_e32 v109, 1.0
	v_mov_b32_e32 v110, 1.0
	v_mov_b32_e32 v111, 1.0
	v_mov_b32_e32 v112, 1.0
	v_mov_b32_e32 v113, 1.0
	s_lshl_b32 s40, s40, 6
	s_add_i32 s40, s40, s41
	v_add_u32_e32 v158, s40, v158
	v_cmp_eq_u32_e32 vcc, 0, v159
	v_ashrrev_i32_e32 v159, 31, v158
	v_lshlrev_b64 v[164:165], 11, v[158:159]
	s_lshl_b32 s94, s99, 2
	s_ashr_i32 s95, s94, 31
	s_ashr_i32 s93, s92, 31
	v_pk_mul_f32 v[166:167], v[140:141], v[124:125]
	v_pk_mul_f32 v[144:145], v[144:145], v[128:129]
	v_pk_mul_f32 v[142:143], v[142:143], v[126:127]
	v_pk_mul_f32 v[140:141], v[138:139], v[122:123]
	v_mul_f32_e32 v138, v143, v143
	v_mul_f32_e32 v139, v145, v145
	v_fmac_f32_e32 v138, v142, v142
	v_fmac_f32_e32 v139, v144, v144
	v_add_f32_e32 v138, v138, v139
	v_mul_f32_e32 v139, v141, v141
	v_fmac_f32_e32 v139, v140, v140
	v_add_f32_e32 v138, v138, v139
	v_mul_f32_e32 v139, v167, v167
	v_fmac_f32_e32 v139, v166, v166
	v_add_f32_e32 v168, v139, v138
	v_cvt_pk_bf16_f32 v138, v142, v143
	v_lshl_add_u64 v[142:143], s[62:63], 0, v[164:165]
	v_cvt_pk_bf16_f32 v139, v144, v145
	v_lshl_add_u64 v[142:143], v[156:157], 1, v[142:143]
	v_pk_mul_f32 v[136:137], v[136:137], v[112:113]
	v_pk_mul_f32 v[134:135], v[134:135], v[110:111]
	v_cvt_pk_bf16_f32 v140, v140, v141
	v_cvt_pk_bf16_f32 v141, v166, v167
	global_store_dwordx4 v[142:143], v[138:141], off
	s_nop 1
	v_pk_mul_f32 v[138:139], v[132:133], v[108:109]
	v_pk_mul_f32 v[132:133], v[130:131], v[106:107]
	v_mul_f32_e32 v130, v135, v135
	v_mul_f32_e32 v131, v137, v137
	v_fmac_f32_e32 v130, v134, v134
	v_fmac_f32_e32 v131, v136, v136
	v_add_f32_e32 v130, v130, v131
	v_mul_f32_e32 v131, v133, v133
	v_fmac_f32_e32 v131, v132, v132
	v_add_f32_e32 v130, v130, v131
	v_mul_f32_e32 v131, v139, v139
	v_fmac_f32_e32 v131, v138, v138
	v_add_f32_e32 v130, v131, v130
	v_cvt_pk_bf16_f32 v131, v136, v137
	v_add_f32_e32 v140, v168, v130
	v_cvt_pk_bf16_f32 v130, v134, v135
	v_cvt_pk_bf16_f32 v132, v132, v133
	v_cvt_pk_bf16_f32 v133, v138, v139
	global_store_dwordx4 v[142:143], v[130:133], off offset:256
	s_nop 1
	v_and_b32_e32 v131, 64, v231
	v_xor_b32_e32 v130, 16, v231
	v_add_u32_e32 v131, 64, v131
	v_cmp_lt_i32_e64 s[40:41], v130, v131
	v_xor_b32_e32 v133, 32, v231
	s_nop 0
	v_cndmask_b32_e64 v130, v231, v130, s[40:41]
	v_lshlrev_b32_e32 v132, 2, v130
	ds_bpermute_b32 v130, v132, v140
	v_cmp_lt_i32_e64 s[40:41], v133, v131
	s_waitcnt lgkmcnt(0)
	v_add_f32_e32 v130, v140, v130
	v_cndmask_b32_e64 v131, v231, v133, s[40:41]
	v_lshlrev_b32_e32 v133, 2, v131
	ds_bpermute_b32 v131, v133, v130
	s_and_saveexec_b64 s[40:41], vcc
	s_cbranch_execz .LBB0_193
	v_lshlrev_b64 v[134:135], 6, v[158:159]
	v_lshl_add_u64 v[134:135], s[76:77], 0, v[134:135]
	v_lshl_add_u64 v[134:135], s[94:95], 2, v[134:135]
	v_lshl_add_u64 v[134:135], s[92:93], 2, v[134:135]
	s_waitcnt lgkmcnt(0)
	v_add_f32_e32 v130, v130, v131
	global_store_dword v[134:135], v130, off
